# s9 + gate_clamp: P1 gate epilogue max(rcp(d),1) -> rcp(clamp(d)) via the fma clamp modifier (bit-identical), 128 v_max per wave per gate tile removed
# baseline (speedup 1.0000x reference)
.LBB0_135:
	s_add_i32 s6, s90, -10
	v_lshl_or_b32 v138, s6, 8, v181
	v_lshl_add_u64 v[176:177], v[138:139], 2, s[48:49]
	global_load_dwordx4 v[156:159], v[176:177], off offset:16
	global_load_dwordx4 v[160:163], v[176:177], off
	global_load_dwordx4 v[226:229], v[176:177], off offset:528
	global_load_dwordx4 v[230:233], v[176:177], off offset:512
	s_lshl_b32 s7, s6, 4
	s_and_b32 s7, s7, 0x3fffffc0
	s_add_i32 s7, s7, s38
	s_lshl_b32 s7, s7, 2
	s_and_b32 s6, s6, 3
	s_or_b32 s6, s7, s6
	s_ashr_i32 s7, s6, 31
	s_lshl_b64 s[6:7], s[6:7], 16
	s_waitcnt vmcnt(2)
	v_pk_mul_f32 v[164:165], v[158:159], s[96:97] op_sel_hi:[1,0]
	v_pk_mul_f32 v[168:169], v[156:157], s[96:97] op_sel_hi:[1,0]
	s_nop 0
	s_nop 0
	v_pk_mul_f32 v[170:171], v[160:161], s[96:97] op_sel_hi:[1,0]
	v_fmamk_f32 v56, v56, 0xbfb8aa3b, v168
	v_fmamk_f32 v120, v120, 0xbfb8aa3b, v168
	v_fmamk_f32 v104, v104, 0xbfb8aa3b, v168
	v_fmamk_f32 v88, v88, 0xbfb8aa3b, v168
	v_fmamk_f32 v72, v72, 0xbfb8aa3b, v168
	v_exp_f32_e32 v56, v56
	v_fmamk_f32 v57, v57, 0xbfb8aa3b, v169
	v_fmamk_f32 v40, v40, 0xbfb8aa3b, v168
	v_fmamk_f32 v24, v24, 0xbfb8aa3b, v168
	v_fmamk_f32 v8, v8, 0xbfb8aa3b, v168
	v_pk_mul_f32 v[166:167], v[162:163], s[96:97] op_sel_hi:[1,0]
	v_exp_f32_e32 v120, v120
	v_fmamk_f32 v121, v121, 0xbfb8aa3b, v169
	v_exp_f32_e32 v104, v104
	v_fmamk_f32 v105, v105, 0xbfb8aa3b, v169
	v_exp_f32_e32 v88, v88
	v_fmamk_f32 v89, v89, 0xbfb8aa3b, v169
	v_exp_f32_e32 v72, v72
	v_fmamk_f32 v73, v73, 0xbfb8aa3b, v169
	v_exp_f32_e32 v57, v57
	v_fmamk_f32 v58, v58, 0xbfb8aa3b, v164
	v_exp_f32_e32 v40, v40
	v_fmamk_f32 v41, v41, 0xbfb8aa3b, v169
	v_exp_f32_e32 v24, v24
	v_fmamk_f32 v25, v25, 0xbfb8aa3b, v169
	v_exp_f32_e32 v8, v8
	v_fmac_f32_e32 v169, 0xbfb8aa3b, v9
	v_exp_f32_e32 v121, v121
	v_fmamk_f32 v122, v122, 0xbfb8aa3b, v164
	v_exp_f32_e32 v105, v105
	v_fmamk_f32 v106, v106, 0xbfb8aa3b, v164
	v_exp_f32_e32 v89, v89
	v_fmamk_f32 v90, v90, 0xbfb8aa3b, v164
	v_exp_f32_e32 v73, v73
	v_fmamk_f32 v74, v74, 0xbfb8aa3b, v164
	v_exp_f32_e32 v58, v58
	v_exp_f32_e32 v41, v41
	v_fmamk_f32 v42, v42, 0xbfb8aa3b, v164
	v_exp_f32_e32 v25, v25
	v_fmamk_f32 v26, v26, 0xbfb8aa3b, v164
	v_exp_f32_e32 v9, v169
	v_exp_f32_e32 v122, v122
	v_exp_f32_e32 v106, v106
	v_exp_f32_e32 v90, v90
	v_exp_f32_e32 v74, v74
	v_exp_f32_e32 v42, v42
	v_exp_f32_e32 v26, v26
	v_fmamk_f32 v10, v10, 0xbfb8aa3b, v164
	v_fma_f32 v56, v56, v205, v205 clamp
	v_exp_f32_e32 v10, v10
	v_fma_f32 v120, v120, v205, v205 clamp
	v_fma_f32 v104, v104, v205, v205 clamp
	v_fma_f32 v88, v88, v205, v205 clamp
	v_fma_f32 v72, v72, v205, v205 clamp
	v_rcp_f32_e32 v56, v56
	v_fma_f32 v57, v57, v205, v205 clamp
	v_fma_f32 v40, v40, v205, v205 clamp
	v_fma_f32 v24, v24, v205, v205 clamp
	v_fma_f32 v8, v8, v205, v205 clamp
	v_rcp_f32_e32 v120, v120
	v_fma_f32 v121, v121, v205, v205 clamp
	v_rcp_f32_e32 v104, v104
	v_fma_f32 v105, v105, v205, v205 clamp
	v_rcp_f32_e32 v88, v88
	v_fma_f32 v89, v89, v205, v205 clamp
	v_rcp_f32_e32 v72, v72
	v_fma_f32 v73, v73, v205, v205 clamp
	v_rcp_f32_e32 v57, v57
	v_fma_f32 v58, v58, v205, v205 clamp
	v_rcp_f32_e32 v40, v40
	v_fma_f32 v41, v41, v205, v205 clamp
	v_rcp_f32_e32 v24, v24
	v_fma_f32 v25, v25, v205, v205 clamp
	v_rcp_f32_e32 v8, v8
	v_fma_f32 v9, v9, v205, v205 clamp
	v_rcp_f32_e32 v121, v121
	v_fma_f32 v122, v122, v205, v205 clamp
	s_waitcnt vmcnt(1)
	v_pk_mul_f32 v[160:161], v[226:227], s[96:97] op_sel_hi:[1,0]
	s_waitcnt vmcnt(0)
	v_pk_mul_f32 v[162:163], v[230:231], s[96:97] op_sel_hi:[1,0]
	v_fmamk_f32 v112, v112, 0xbfb8aa3b, v160
	v_fmamk_f32 v96, v96, 0xbfb8aa3b, v160
	v_fmamk_f32 v80, v80, 0xbfb8aa3b, v160
	v_fmamk_f32 v64, v64, 0xbfb8aa3b, v160
	v_fmamk_f32 v48, v48, 0xbfb8aa3b, v160
	v_fmamk_f32 v32, v32, 0xbfb8aa3b, v160
	v_fmamk_f32 v16, v16, 0xbfb8aa3b, v160
	v_fmamk_f32 v0, v0, 0xbfb8aa3b, v160
	v_pk_mul_f32 v[156:157], v[228:229], s[96:97] op_sel_hi:[1,0]
	v_exp_f32_e32 v112, v112
	v_fmamk_f32 v113, v113, 0xbfb8aa3b, v161
	v_exp_f32_e32 v96, v96
	v_fmamk_f32 v97, v97, 0xbfb8aa3b, v161
	v_exp_f32_e32 v80, v80
	v_fmamk_f32 v81, v81, 0xbfb8aa3b, v161
	v_exp_f32_e32 v64, v64
	v_fmamk_f32 v65, v65, 0xbfb8aa3b, v161
	v_exp_f32_e32 v48, v48
	v_fmamk_f32 v49, v49, 0xbfb8aa3b, v161
	v_exp_f32_e32 v32, v32
	v_fmamk_f32 v33, v33, 0xbfb8aa3b, v161
	v_exp_f32_e32 v16, v16
	v_fmamk_f32 v17, v17, 0xbfb8aa3b, v161
	v_exp_f32_e32 v0, v0
	v_fmac_f32_e32 v161, 0xbfb8aa3b, v1
	v_exp_f32_e32 v113, v113
	v_fmamk_f32 v114, v114, 0xbfb8aa3b, v156
	v_exp_f32_e32 v97, v97
	v_fmamk_f32 v98, v98, 0xbfb8aa3b, v156
	v_exp_f32_e32 v81, v81
	v_fmamk_f32 v82, v82, 0xbfb8aa3b, v156
	v_exp_f32_e32 v65, v65
	v_fmamk_f32 v66, v66, 0xbfb8aa3b, v156
	v_exp_f32_e32 v49, v49
	v_fmamk_f32 v50, v50, 0xbfb8aa3b, v156
	v_exp_f32_e32 v33, v33
	v_fmamk_f32 v34, v34, 0xbfb8aa3b, v156
	v_exp_f32_e32 v17, v17
	v_fmamk_f32 v18, v18, 0xbfb8aa3b, v156
	v_exp_f32_e32 v1, v161
	v_exp_f32_e32 v114, v114
	v_exp_f32_e32 v98, v98
	v_exp_f32_e32 v82, v82
	v_exp_f32_e32 v66, v66
	v_exp_f32_e32 v50, v50
	v_exp_f32_e32 v34, v34
	v_exp_f32_e32 v18, v18
	v_fmamk_f32 v2, v2, 0xbfb8aa3b, v156
	v_exp_f32_e32 v2, v2
	v_fma_f32 v112, v112, v205, v205 clamp
	v_fma_f32 v96, v96, v205, v205 clamp
	v_fma_f32 v80, v80, v205, v205 clamp
	v_fma_f32 v64, v64, v205, v205 clamp
	v_fma_f32 v48, v48, v205, v205 clamp
	v_fma_f32 v32, v32, v205, v205 clamp
	v_fma_f32 v16, v16, v205, v205 clamp
	v_fma_f32 v0, v0, v205, v205 clamp
	v_rcp_f32_e32 v112, v112
	v_fma_f32 v113, v113, v205, v205 clamp
	v_rcp_f32_e32 v96, v96
	v_fma_f32 v97, v97, v205, v205 clamp
	v_rcp_f32_e32 v80, v80
	v_fma_f32 v81, v81, v205, v205 clamp
	v_rcp_f32_e32 v64, v64
	v_fma_f32 v65, v65, v205, v205 clamp
	v_rcp_f32_e32 v48, v48
	v_fma_f32 v49, v49, v205, v205 clamp
	v_rcp_f32_e32 v32, v32
	v_fma_f32 v33, v33, v205, v205 clamp
	v_rcp_f32_e32 v16, v16
	v_fma_f32 v17, v17, v205, v205 clamp
	v_rcp_f32_e32 v0, v0
	v_fma_f32 v1, v1, v205, v205 clamp
	v_rcp_f32_e32 v113, v113
	v_fma_f32 v114, v114, v205, v205 clamp
	v_rcp_f32_e32 v105, v105
	v_fma_f32 v106, v106, v205, v205 clamp
	v_rcp_f32_e32 v97, v97
	v_fma_f32 v98, v98, v205, v205 clamp
	v_rcp_f32_e32 v89, v89
	v_fma_f32 v90, v90, v205, v205 clamp
	v_rcp_f32_e32 v81, v81
	v_fma_f32 v82, v82, v205, v205 clamp
	v_rcp_f32_e32 v73, v73
	v_fma_f32 v74, v74, v205, v205 clamp
	v_rcp_f32_e32 v65, v65
	v_fma_f32 v66, v66, v205, v205 clamp
	v_rcp_f32_e32 v58, v58
	v_rcp_f32_e32 v49, v49
	v_fma_f32 v50, v50, v205, v205 clamp
	v_rcp_f32_e32 v41, v41
	v_fma_f32 v42, v42, v205, v205 clamp
	v_rcp_f32_e32 v33, v33
	v_fma_f32 v34, v34, v205, v205 clamp
	v_rcp_f32_e32 v25, v25
	v_fma_f32 v26, v26, v205, v205 clamp
	v_rcp_f32_e32 v17, v17
	v_fma_f32 v18, v18, v205, v205 clamp
	v_rcp_f32_e32 v9, v9
	v_rcp_f32_e32 v1, v1
	v_rcp_f32_e32 v122, v122
	v_rcp_f32_e32 v114, v114
	v_rcp_f32_e32 v106, v106
	v_rcp_f32_e32 v98, v98
	v_rcp_f32_e32 v90, v90
	v_rcp_f32_e32 v82, v82
	v_rcp_f32_e32 v74, v74
	v_rcp_f32_e32 v66, v66
	v_rcp_f32_e32 v50, v50
	v_rcp_f32_e32 v42, v42
	v_rcp_f32_e32 v34, v34
	v_rcp_f32_e32 v26, v26
	v_rcp_f32_e32 v18, v18
	v_fma_f32 v10, v10, v205, v205 clamp
	v_fma_f32 v2, v2, v205, v205 clamp
	v_rcp_f32_e32 v10, v10
	v_rcp_f32_e32 v2, v2
	v_fmamk_f32 v60, v60, 0xbfb8aa3b, v170
	v_rndne_f32_e32 v56, v56
	v_fmamk_f32 v124, v124, 0xbfb8aa3b, v170
	v_rndne_f32_e32 v120, v120
	v_fmamk_f32 v116, v116, 0xbfb8aa3b, v162
	v_rndne_f32_e32 v112, v112
	v_fmamk_f32 v108, v108, 0xbfb8aa3b, v170
	v_rndne_f32_e32 v104, v104
	v_fmamk_f32 v100, v100, 0xbfb8aa3b, v162
	v_rndne_f32_e32 v96, v96
	v_fmamk_f32 v92, v92, 0xbfb8aa3b, v170
	v_rndne_f32_e32 v88, v88
	v_fmamk_f32 v84, v84, 0xbfb8aa3b, v162
	v_rndne_f32_e32 v80, v80
	v_fmamk_f32 v76, v76, 0xbfb8aa3b, v170
	v_rndne_f32_e32 v72, v72
	v_fmamk_f32 v68, v68, 0xbfb8aa3b, v162
	v_rndne_f32_e32 v64, v64
	v_exp_f32_e32 v60, v60
	v_cvt_pk_u8_f32 v56, v56, 0, 0
	v_fmamk_f32 v61, v61, 0xbfb8aa3b, v171
	v_rndne_f32_e32 v57, v57
	v_fmamk_f32 v52, v52, 0xbfb8aa3b, v162
	v_rndne_f32_e32 v48, v48
	v_fmamk_f32 v44, v44, 0xbfb8aa3b, v170
	v_rndne_f32_e32 v40, v40
	v_fmamk_f32 v36, v36, 0xbfb8aa3b, v162
	v_rndne_f32_e32 v32, v32
	v_fmamk_f32 v28, v28, 0xbfb8aa3b, v170
	v_rndne_f32_e32 v24, v24
	v_fmamk_f32 v20, v20, 0xbfb8aa3b, v162
	v_rndne_f32_e32 v16, v16
	v_fmamk_f32 v12, v12, 0xbfb8aa3b, v170
	v_rndne_f32_e32 v8, v8
	v_fmamk_f32 v4, v4, 0xbfb8aa3b, v162
	v_rndne_f32_e32 v0, v0
	v_pk_mul_f32 v[158:159], v[232:233], s[96:97] op_sel_hi:[1,0]
	v_exp_f32_e32 v124, v124
	v_cvt_pk_u8_f32 v120, v120, 0, 0
	v_fmamk_f32 v125, v125, 0xbfb8aa3b, v171
	v_rndne_f32_e32 v121, v121
	v_exp_f32_e32 v116, v116
	v_cvt_pk_u8_f32 v112, v112, 0, 0
	v_fmamk_f32 v117, v117, 0xbfb8aa3b, v163
	v_rndne_f32_e32 v113, v113
	v_exp_f32_e32 v108, v108
	v_cvt_pk_u8_f32 v104, v104, 0, 0
	v_fmamk_f32 v109, v109, 0xbfb8aa3b, v171
	v_rndne_f32_e32 v105, v105
	v_exp_f32_e32 v100, v100
	v_cvt_pk_u8_f32 v96, v96, 0, 0
	v_fmamk_f32 v101, v101, 0xbfb8aa3b, v163
	v_rndne_f32_e32 v97, v97
	v_exp_f32_e32 v92, v92
	v_cvt_pk_u8_f32 v88, v88, 0, 0
	v_fmamk_f32 v93, v93, 0xbfb8aa3b, v171
	v_rndne_f32_e32 v89, v89
	v_exp_f32_e32 v84, v84
	v_cvt_pk_u8_f32 v80, v80, 0, 0
	v_fmamk_f32 v85, v85, 0xbfb8aa3b, v163
	v_rndne_f32_e32 v81, v81
	v_exp_f32_e32 v76, v76
	v_cvt_pk_u8_f32 v72, v72, 0, 0
	v_fmamk_f32 v77, v77, 0xbfb8aa3b, v171
	v_rndne_f32_e32 v73, v73
	v_exp_f32_e32 v68, v68
	v_cvt_pk_u8_f32 v64, v64, 0, 0
	v_fmamk_f32 v69, v69, 0xbfb8aa3b, v163
	v_rndne_f32_e32 v65, v65
	v_exp_f32_e32 v61, v61
	v_cvt_pk_u8_f32 v56, v57, 1, v56
	v_fmamk_f32 v57, v62, 0xbfb8aa3b, v166
	v_rndne_f32_e32 v58, v58
	v_exp_f32_e32 v52, v52
	v_cvt_pk_u8_f32 v48, v48, 0, 0
	v_fmamk_f32 v53, v53, 0xbfb8aa3b, v163
	v_rndne_f32_e32 v49, v49
	v_exp_f32_e32 v44, v44
	v_cvt_pk_u8_f32 v40, v40, 0, 0
	v_fmamk_f32 v45, v45, 0xbfb8aa3b, v171
	v_rndne_f32_e32 v41, v41
	v_exp_f32_e32 v36, v36
	v_cvt_pk_u8_f32 v32, v32, 0, 0
	v_fmamk_f32 v37, v37, 0xbfb8aa3b, v163
	v_rndne_f32_e32 v33, v33
	v_exp_f32_e32 v28, v28
	v_cvt_pk_u8_f32 v24, v24, 0, 0
	v_fmamk_f32 v29, v29, 0xbfb8aa3b, v171
	v_rndne_f32_e32 v25, v25
	v_exp_f32_e32 v20, v20
	v_cvt_pk_u8_f32 v16, v16, 0, 0
	v_fmamk_f32 v21, v21, 0xbfb8aa3b, v163
	v_rndne_f32_e32 v17, v17
	v_exp_f32_e32 v12, v12
	v_cvt_pk_u8_f32 v8, v8, 0, 0
	v_fmac_f32_e32 v171, 0xbfb8aa3b, v13
	v_rndne_f32_e32 v9, v9
	v_exp_f32_e32 v4, v4
	v_cvt_pk_u8_f32 v0, v0, 0, 0
	v_fmac_f32_e32 v163, 0xbfb8aa3b, v5
	v_rndne_f32_e32 v1, v1
	v_exp_f32_e32 v125, v125
	v_cvt_pk_u8_f32 v120, v121, 1, v120
	v_fmamk_f32 v121, v126, 0xbfb8aa3b, v166
	v_rndne_f32_e32 v122, v122
	v_exp_f32_e32 v117, v117
	v_cvt_pk_u8_f32 v112, v113, 1, v112
	v_fmamk_f32 v113, v118, 0xbfb8aa3b, v158
	v_rndne_f32_e32 v114, v114
	v_exp_f32_e32 v109, v109
	v_cvt_pk_u8_f32 v104, v105, 1, v104
	v_fmamk_f32 v105, v110, 0xbfb8aa3b, v166
	v_rndne_f32_e32 v106, v106
	v_exp_f32_e32 v101, v101
	v_cvt_pk_u8_f32 v96, v97, 1, v96
	v_fmamk_f32 v97, v102, 0xbfb8aa3b, v158
	v_rndne_f32_e32 v98, v98
	v_exp_f32_e32 v93, v93
	v_cvt_pk_u8_f32 v88, v89, 1, v88
	v_fmamk_f32 v89, v94, 0xbfb8aa3b, v166
	v_rndne_f32_e32 v90, v90
	v_exp_f32_e32 v85, v85
	v_cvt_pk_u8_f32 v80, v81, 1, v80
	v_fmamk_f32 v81, v86, 0xbfb8aa3b, v158
	v_rndne_f32_e32 v82, v82
	v_exp_f32_e32 v77, v77
	v_cvt_pk_u8_f32 v72, v73, 1, v72
	v_fmamk_f32 v73, v78, 0xbfb8aa3b, v166
	v_rndne_f32_e32 v74, v74
	v_exp_f32_e32 v69, v69
	v_cvt_pk_u8_f32 v64, v65, 1, v64
	v_fmamk_f32 v65, v70, 0xbfb8aa3b, v158
	v_rndne_f32_e32 v66, v66
	v_exp_f32_e32 v57, v57
	v_cvt_pk_u8_f32 v58, v58, 2, v56
	v_fmamk_f32 v56, v63, 0xbfb8aa3b, v167
	v_fmamk_f32 v59, v59, 0xbfb8aa3b, v165
	v_exp_f32_e32 v53, v53
	v_cvt_pk_u8_f32 v48, v49, 1, v48
	v_fmamk_f32 v49, v54, 0xbfb8aa3b, v158
	v_rndne_f32_e32 v50, v50
	v_fmamk_f32 v51, v51, 0xbfb8aa3b, v157
	v_exp_f32_e32 v45, v45
	v_cvt_pk_u8_f32 v40, v41, 1, v40
	v_fmamk_f32 v41, v46, 0xbfb8aa3b, v166
	v_rndne_f32_e32 v42, v42
	v_exp_f32_e32 v37, v37
	v_cvt_pk_u8_f32 v32, v33, 1, v32
	v_fmamk_f32 v33, v38, 0xbfb8aa3b, v158
	v_rndne_f32_e32 v34, v34
	v_exp_f32_e32 v29, v29
	v_cvt_pk_u8_f32 v24, v25, 1, v24
	v_fmamk_f32 v25, v30, 0xbfb8aa3b, v166
	v_rndne_f32_e32 v26, v26
	v_exp_f32_e32 v21, v21
	v_cvt_pk_u8_f32 v16, v17, 1, v16
	v_fmamk_f32 v17, v22, 0xbfb8aa3b, v158
	v_rndne_f32_e32 v18, v18
	v_exp_f32_e32 v13, v171
	v_cvt_pk_u8_f32 v8, v9, 1, v8
	v_fmamk_f32 v9, v14, 0xbfb8aa3b, v166
	v_exp_f32_e32 v5, v163
	v_cvt_pk_u8_f32 v0, v1, 1, v0
	v_fmamk_f32 v1, v6, 0xbfb8aa3b, v158
	v_exp_f32_e32 v121, v121
	v_cvt_pk_u8_f32 v122, v122, 2, v120
	v_fmamk_f32 v120, v127, 0xbfb8aa3b, v167
	v_fmamk_f32 v123, v123, 0xbfb8aa3b, v165
	v_exp_f32_e32 v113, v113
	v_cvt_pk_u8_f32 v112, v114, 2, v112
	v_fmamk_f32 v114, v119, 0xbfb8aa3b, v159
	v_fmamk_f32 v115, v115, 0xbfb8aa3b, v157
	v_exp_f32_e32 v105, v105
	v_cvt_pk_u8_f32 v106, v106, 2, v104
	v_fmamk_f32 v104, v111, 0xbfb8aa3b, v167
	v_fmamk_f32 v107, v107, 0xbfb8aa3b, v165
	v_exp_f32_e32 v97, v97
	v_cvt_pk_u8_f32 v96, v98, 2, v96
	v_fmamk_f32 v98, v103, 0xbfb8aa3b, v159
	v_fmamk_f32 v99, v99, 0xbfb8aa3b, v157
	v_exp_f32_e32 v89, v89
	v_cvt_pk_u8_f32 v90, v90, 2, v88
	v_fmamk_f32 v88, v95, 0xbfb8aa3b, v167
	v_fmamk_f32 v91, v91, 0xbfb8aa3b, v165
	v_exp_f32_e32 v81, v81
	v_cvt_pk_u8_f32 v80, v82, 2, v80
	v_fmamk_f32 v82, v87, 0xbfb8aa3b, v159
	v_fmamk_f32 v83, v83, 0xbfb8aa3b, v157
	v_exp_f32_e32 v73, v73
	v_cvt_pk_u8_f32 v74, v74, 2, v72
	v_fmamk_f32 v72, v79, 0xbfb8aa3b, v167
	v_fmamk_f32 v75, v75, 0xbfb8aa3b, v165
	v_exp_f32_e32 v65, v65
	v_cvt_pk_u8_f32 v64, v66, 2, v64
	v_fmamk_f32 v66, v71, 0xbfb8aa3b, v159
	v_fmamk_f32 v67, v67, 0xbfb8aa3b, v157
	v_exp_f32_e32 v56, v56
	v_exp_f32_e32 v59, v59
	v_exp_f32_e32 v49, v49
	v_cvt_pk_u8_f32 v48, v50, 2, v48
	v_fmamk_f32 v50, v55, 0xbfb8aa3b, v159
	v_exp_f32_e32 v51, v51
	v_exp_f32_e32 v41, v41
	v_cvt_pk_u8_f32 v42, v42, 2, v40
	v_fmamk_f32 v40, v47, 0xbfb8aa3b, v167
	v_fmamk_f32 v43, v43, 0xbfb8aa3b, v165
	v_exp_f32_e32 v33, v33
	v_cvt_pk_u8_f32 v32, v34, 2, v32
	v_fmamk_f32 v34, v39, 0xbfb8aa3b, v159
	v_fmamk_f32 v35, v35, 0xbfb8aa3b, v157
	v_exp_f32_e32 v25, v25
	v_cvt_pk_u8_f32 v26, v26, 2, v24
	v_fmamk_f32 v24, v31, 0xbfb8aa3b, v167
	v_fmamk_f32 v27, v27, 0xbfb8aa3b, v165
	v_exp_f32_e32 v17, v17
	v_cvt_pk_u8_f32 v16, v18, 2, v16
	v_fmamk_f32 v18, v23, 0xbfb8aa3b, v159
	v_fmamk_f32 v19, v19, 0xbfb8aa3b, v157
	v_exp_f32_e32 v9, v9
	v_rndne_f32_e32 v10, v10
	v_fmac_f32_e32 v167, 0xbfb8aa3b, v15
	v_fmac_f32_e32 v165, 0xbfb8aa3b, v11
	v_exp_f32_e32 v1, v1
	v_rndne_f32_e32 v2, v2
	v_fmac_f32_e32 v159, 0xbfb8aa3b, v7
	v_fmac_f32_e32 v157, 0xbfb8aa3b, v3
	v_exp_f32_e32 v120, v120
	v_exp_f32_e32 v123, v123
	v_exp_f32_e32 v114, v114
	v_exp_f32_e32 v115, v115
	v_exp_f32_e32 v104, v104
	v_exp_f32_e32 v107, v107
	v_exp_f32_e32 v98, v98
	v_exp_f32_e32 v99, v99
	v_exp_f32_e32 v88, v88
	v_exp_f32_e32 v91, v91
	v_exp_f32_e32 v82, v82
	v_exp_f32_e32 v83, v83
	v_exp_f32_e32 v72, v72
	v_exp_f32_e32 v75, v75
	v_exp_f32_e32 v66, v66
	v_exp_f32_e32 v67, v67
	v_fma_f32 v60, v60, v205, v205 clamp
	v_exp_f32_e32 v50, v50
	v_exp_f32_e32 v40, v40
	v_exp_f32_e32 v43, v43
	v_exp_f32_e32 v34, v34
	v_exp_f32_e32 v35, v35
	v_exp_f32_e32 v24, v24
	v_exp_f32_e32 v27, v27
	v_exp_f32_e32 v18, v18
	v_exp_f32_e32 v19, v19
	v_cvt_pk_u8_f32 v10, v10, 2, v8
	v_exp_f32_e32 v8, v167
	v_exp_f32_e32 v11, v165
	v_cvt_pk_u8_f32 v0, v2, 2, v0
	v_exp_f32_e32 v2, v159
	v_exp_f32_e32 v3, v157
	v_fma_f32 v124, v124, v205, v205 clamp
	v_fma_f32 v116, v116, v205, v205 clamp
	v_fma_f32 v108, v108, v205, v205 clamp
	v_fma_f32 v100, v100, v205, v205 clamp
	v_fma_f32 v92, v92, v205, v205 clamp
	v_fma_f32 v84, v84, v205, v205 clamp
	v_fma_f32 v76, v76, v205, v205 clamp
	v_fma_f32 v68, v68, v205, v205 clamp
	v_rcp_f32_e32 v60, v60
	v_fma_f32 v61, v61, v205, v205 clamp
	v_fma_f32 v52, v52, v205, v205 clamp
	v_fma_f32 v44, v44, v205, v205 clamp
	v_fma_f32 v36, v36, v205, v205 clamp
	v_fma_f32 v28, v28, v205, v205 clamp
	v_fma_f32 v20, v20, v205, v205 clamp
	v_fma_f32 v12, v12, v205, v205 clamp
	v_fma_f32 v4, v4, v205, v205 clamp
	v_rcp_f32_e32 v124, v124
	v_fma_f32 v125, v125, v205, v205 clamp
	v_rcp_f32_e32 v116, v116
	v_fma_f32 v117, v117, v205, v205 clamp
	v_rcp_f32_e32 v108, v108
	v_fma_f32 v109, v109, v205, v205 clamp
	v_rcp_f32_e32 v100, v100
	v_fma_f32 v101, v101, v205, v205 clamp
	v_rcp_f32_e32 v92, v92
	v_fma_f32 v93, v93, v205, v205 clamp
	v_rcp_f32_e32 v84, v84
	v_fma_f32 v85, v85, v205, v205 clamp
	v_rcp_f32_e32 v76, v76
	v_fma_f32 v77, v77, v205, v205 clamp
	v_rcp_f32_e32 v68, v68
	v_fma_f32 v69, v69, v205, v205 clamp
	v_rcp_f32_e32 v61, v61
	v_fma_f32 v57, v57, v205, v205 clamp
	v_rcp_f32_e32 v52, v52
	v_fma_f32 v53, v53, v205, v205 clamp
	v_rcp_f32_e32 v44, v44
	v_fma_f32 v45, v45, v205, v205 clamp
	v_rcp_f32_e32 v36, v36
	v_fma_f32 v37, v37, v205, v205 clamp
	v_rcp_f32_e32 v28, v28
	v_fma_f32 v29, v29, v205, v205 clamp
	v_rcp_f32_e32 v20, v20
	v_fma_f32 v21, v21, v205, v205 clamp
	v_rcp_f32_e32 v12, v12
	v_fma_f32 v13, v13, v205, v205 clamp
	v_rcp_f32_e32 v4, v4
	v_fma_f32 v5, v5, v205, v205 clamp
	v_rcp_f32_e32 v125, v125
	v_fma_f32 v121, v121, v205, v205 clamp
	v_rcp_f32_e32 v117, v117
	v_fma_f32 v113, v113, v205, v205 clamp
	v_rcp_f32_e32 v109, v109
	v_fma_f32 v105, v105, v205, v205 clamp
	v_rcp_f32_e32 v101, v101
	v_fma_f32 v97, v97, v205, v205 clamp
	v_rcp_f32_e32 v93, v93
	v_fma_f32 v89, v89, v205, v205 clamp
	v_rcp_f32_e32 v85, v85
	v_fma_f32 v81, v81, v205, v205 clamp
	v_rcp_f32_e32 v77, v77
	v_fma_f32 v73, v73, v205, v205 clamp
	v_rcp_f32_e32 v69, v69
	v_fma_f32 v65, v65, v205, v205 clamp
	v_rcp_f32_e32 v57, v57
	v_fma_f32 v56, v56, v205, v205 clamp
	v_fma_f32 v59, v59, v205, v205 clamp
	v_rcp_f32_e32 v53, v53
	v_fma_f32 v49, v49, v205, v205 clamp
	v_fma_f32 v51, v51, v205, v205 clamp
	v_rcp_f32_e32 v45, v45
	v_fma_f32 v41, v41, v205, v205 clamp
	v_rcp_f32_e32 v37, v37
	v_fma_f32 v33, v33, v205, v205 clamp
	v_rcp_f32_e32 v29, v29
	v_fma_f32 v25, v25, v205, v205 clamp
	v_rcp_f32_e32 v21, v21
	v_fma_f32 v17, v17, v205, v205 clamp
	v_rcp_f32_e32 v13, v13
	v_fma_f32 v9, v9, v205, v205 clamp
	v_rcp_f32_e32 v5, v5
	v_fma_f32 v1, v1, v205, v205 clamp
	v_rcp_f32_e32 v121, v121
	v_fma_f32 v120, v120, v205, v205 clamp
	v_fma_f32 v123, v123, v205, v205 clamp
	v_rcp_f32_e32 v113, v113
	v_fma_f32 v114, v114, v205, v205 clamp
	v_fma_f32 v115, v115, v205, v205 clamp
	v_rcp_f32_e32 v105, v105
	v_fma_f32 v104, v104, v205, v205 clamp
	v_fma_f32 v107, v107, v205, v205 clamp
	v_rcp_f32_e32 v97, v97
	v_fma_f32 v98, v98, v205, v205 clamp
	v_fma_f32 v99, v99, v205, v205 clamp
	v_rcp_f32_e32 v89, v89
	v_fma_f32 v88, v88, v205, v205 clamp
	v_fma_f32 v91, v91, v205, v205 clamp
	v_rcp_f32_e32 v81, v81
	v_fma_f32 v82, v82, v205, v205 clamp
	v_fma_f32 v83, v83, v205, v205 clamp
	v_rcp_f32_e32 v73, v73
	v_fma_f32 v72, v72, v205, v205 clamp
	v_fma_f32 v75, v75, v205, v205 clamp
	v_rcp_f32_e32 v65, v65
	v_fma_f32 v66, v66, v205, v205 clamp
	v_fma_f32 v67, v67, v205, v205 clamp
	v_rcp_f32_e32 v56, v56
	v_rcp_f32_e32 v59, v59
	v_rcp_f32_e32 v49, v49
	v_fma_f32 v50, v50, v205, v205 clamp
	v_rcp_f32_e32 v51, v51
	v_rcp_f32_e32 v41, v41
	v_fma_f32 v40, v40, v205, v205 clamp
	v_fma_f32 v43, v43, v205, v205 clamp
	v_rcp_f32_e32 v33, v33
	v_fma_f32 v34, v34, v205, v205 clamp
	v_fma_f32 v35, v35, v205, v205 clamp
	v_rcp_f32_e32 v25, v25
	v_fma_f32 v24, v24, v205, v205 clamp
	v_fma_f32 v27, v27, v205, v205 clamp
	v_rcp_f32_e32 v17, v17
	v_fma_f32 v18, v18, v205, v205 clamp
	v_fma_f32 v19, v19, v205, v205 clamp
	v_rcp_f32_e32 v9, v9
	v_fma_f32 v8, v8, v205, v205 clamp
	v_fma_f32 v11, v11, v205, v205 clamp
	v_rcp_f32_e32 v1, v1
	v_fma_f32 v2, v2, v205, v205 clamp
	v_fma_f32 v3, v3, v205, v205 clamp
	v_rcp_f32_e32 v120, v120
	v_rcp_f32_e32 v123, v123
	v_rcp_f32_e32 v114, v114
	v_rcp_f32_e32 v115, v115
	v_rcp_f32_e32 v104, v104
	v_rcp_f32_e32 v107, v107
	v_rcp_f32_e32 v98, v98
	v_rcp_f32_e32 v99, v99
	v_rcp_f32_e32 v88, v88
	v_rcp_f32_e32 v91, v91
	v_rcp_f32_e32 v82, v82
	v_rcp_f32_e32 v83, v83
	v_rcp_f32_e32 v72, v72
	v_rcp_f32_e32 v75, v75
	v_rcp_f32_e32 v66, v66
	v_rcp_f32_e32 v67, v67
	v_rcp_f32_e32 v50, v50
	v_rcp_f32_e32 v40, v40
	v_rcp_f32_e32 v43, v43
	v_rcp_f32_e32 v34, v34
	v_rcp_f32_e32 v35, v35
	v_rcp_f32_e32 v24, v24
	v_rcp_f32_e32 v27, v27
	v_rcp_f32_e32 v18, v18
	v_rcp_f32_e32 v19, v19
	v_rcp_f32_e32 v8, v8
	v_rcp_f32_e32 v11, v11
	v_rcp_f32_e32 v2, v2
	v_rcp_f32_e32 v3, v3
	v_rndne_f32_e32 v60, v60
	v_rndne_f32_e32 v124, v124
	v_rndne_f32_e32 v116, v116
	v_rndne_f32_e32 v108, v108
	v_rndne_f32_e32 v100, v100
	v_rndne_f32_e32 v92, v92
	v_rndne_f32_e32 v84, v84
	v_rndne_f32_e32 v76, v76
	v_rndne_f32_e32 v68, v68
	v_cvt_pk_u8_f32 v60, v60, 0, 0
	v_rndne_f32_e32 v61, v61
	v_rndne_f32_e32 v52, v52
	v_rndne_f32_e32 v44, v44
	v_rndne_f32_e32 v36, v36
	v_rndne_f32_e32 v28, v28
	v_rndne_f32_e32 v20, v20
	v_rndne_f32_e32 v12, v12
	v_rndne_f32_e32 v4, v4
	v_cvt_pk_u8_f32 v124, v124, 0, 0
	v_rndne_f32_e32 v125, v125
	v_cvt_pk_u8_f32 v116, v116, 0, 0
	v_rndne_f32_e32 v117, v117
	v_cvt_pk_u8_f32 v108, v108, 0, 0
	v_rndne_f32_e32 v109, v109
	v_cvt_pk_u8_f32 v100, v100, 0, 0
	v_rndne_f32_e32 v101, v101
	v_cvt_pk_u8_f32 v92, v92, 0, 0
	v_rndne_f32_e32 v93, v93
	v_cvt_pk_u8_f32 v84, v84, 0, 0
	v_rndne_f32_e32 v85, v85
	v_cvt_pk_u8_f32 v76, v76, 0, 0
	v_rndne_f32_e32 v77, v77
	v_cvt_pk_u8_f32 v68, v68, 0, 0
	v_rndne_f32_e32 v69, v69
	v_cvt_pk_u8_f32 v60, v61, 1, v60
	v_rndne_f32_e32 v57, v57
	v_cvt_pk_u8_f32 v52, v52, 0, 0
	v_rndne_f32_e32 v53, v53
	v_cvt_pk_u8_f32 v44, v44, 0, 0
	v_rndne_f32_e32 v45, v45
	v_cvt_pk_u8_f32 v36, v36, 0, 0
	v_rndne_f32_e32 v37, v37
	v_cvt_pk_u8_f32 v28, v28, 0, 0
	v_rndne_f32_e32 v29, v29
	v_cvt_pk_u8_f32 v20, v20, 0, 0
	v_rndne_f32_e32 v21, v21
	v_cvt_pk_u8_f32 v12, v12, 0, 0
	v_rndne_f32_e32 v13, v13
	v_cvt_pk_u8_f32 v4, v4, 0, 0
	v_rndne_f32_e32 v5, v5
	v_lshl_add_u64 v[172:173], v[140:141], 0, s[6:7]
	v_cvt_pk_u8_f32 v124, v125, 1, v124
	v_rndne_f32_e32 v121, v121
	v_cvt_pk_u8_f32 v116, v117, 1, v116
	v_rndne_f32_e32 v113, v113
	v_cvt_pk_u8_f32 v108, v109, 1, v108
	v_rndne_f32_e32 v105, v105
	v_cvt_pk_u8_f32 v100, v101, 1, v100
	v_rndne_f32_e32 v97, v97
	v_cvt_pk_u8_f32 v92, v93, 1, v92
	v_rndne_f32_e32 v89, v89
	v_cvt_pk_u8_f32 v84, v85, 1, v84
	v_rndne_f32_e32 v81, v81
	v_cvt_pk_u8_f32 v76, v77, 1, v76
	v_rndne_f32_e32 v73, v73
	v_cvt_pk_u8_f32 v68, v69, 1, v68
	v_rndne_f32_e32 v65, v65
	v_cvt_pk_u8_f32 v57, v57, 2, v60
	v_rndne_f32_e32 v56, v56
	v_rndne_f32_e32 v59, v59
	v_cvt_pk_u8_f32 v52, v53, 1, v52
	v_rndne_f32_e32 v49, v49
	v_rndne_f32_e32 v51, v51
	s_movk_i32 s6, 0x1000
	v_cvt_pk_u8_f32 v44, v45, 1, v44
	v_rndne_f32_e32 v41, v41
	v_cvt_pk_u8_f32 v36, v37, 1, v36
	v_rndne_f32_e32 v33, v33
	v_cvt_pk_u8_f32 v28, v29, 1, v28
	v_rndne_f32_e32 v25, v25
	v_cvt_pk_u8_f32 v20, v21, 1, v20
	v_rndne_f32_e32 v17, v17
	v_cvt_pk_u8_f32 v12, v13, 1, v12
	v_rndne_f32_e32 v9, v9
	v_cvt_pk_u8_f32 v4, v5, 1, v4
	v_rndne_f32_e32 v1, v1
	v_cvt_pk_u8_f32 v121, v121, 2, v124
	v_rndne_f32_e32 v120, v120
	v_rndne_f32_e32 v123, v123
	v_cvt_pk_u8_f32 v113, v113, 2, v116
	v_rndne_f32_e32 v114, v114
	v_rndne_f32_e32 v115, v115
	v_cvt_pk_u8_f32 v105, v105, 2, v108
	v_rndne_f32_e32 v104, v104
	v_rndne_f32_e32 v107, v107
	v_cvt_pk_u8_f32 v97, v97, 2, v100
	v_rndne_f32_e32 v98, v98
	v_rndne_f32_e32 v99, v99
	v_cvt_pk_u8_f32 v89, v89, 2, v92
	v_rndne_f32_e32 v88, v88
	v_rndne_f32_e32 v91, v91
	v_cvt_pk_u8_f32 v81, v81, 2, v84
	v_rndne_f32_e32 v82, v82
	v_rndne_f32_e32 v83, v83
	v_cvt_pk_u8_f32 v73, v73, 2, v76
	v_rndne_f32_e32 v72, v72
	v_rndne_f32_e32 v75, v75
	v_cvt_pk_u8_f32 v65, v65, 2, v68
	v_rndne_f32_e32 v66, v66
	v_rndne_f32_e32 v67, v67
	v_cvt_pk_u8_f32 v56, v56, 3, v57
	v_cvt_pk_u8_f32 v57, v59, 3, v58
	v_cvt_pk_u8_f32 v49, v49, 2, v52
	v_rndne_f32_e32 v50, v50
	v_cvt_pk_u8_f32 v59, v51, 3, v48
	v_add_co_u32_e32 v48, vcc, s6, v172
	v_cvt_pk_u8_f32 v41, v41, 2, v44
	v_rndne_f32_e32 v40, v40
	v_rndne_f32_e32 v43, v43
	v_cvt_pk_u8_f32 v33, v33, 2, v36
	v_rndne_f32_e32 v34, v34
	v_rndne_f32_e32 v35, v35
	v_cvt_pk_u8_f32 v25, v25, 2, v28
	v_rndne_f32_e32 v24, v24
	v_rndne_f32_e32 v27, v27
	v_cvt_pk_u8_f32 v17, v17, 2, v20
	v_rndne_f32_e32 v18, v18
	v_rndne_f32_e32 v19, v19
	v_cvt_pk_u8_f32 v9, v9, 2, v12
	v_rndne_f32_e32 v8, v8
	v_rndne_f32_e32 v11, v11
	v_cvt_pk_u8_f32 v1, v1, 2, v4
	v_rndne_f32_e32 v2, v2
	v_rndne_f32_e32 v3, v3
	v_cvt_pk_u8_f32 v120, v120, 3, v121
	v_cvt_pk_u8_f32 v121, v123, 3, v122
	v_cvt_pk_u8_f32 v122, v114, 3, v113
	v_cvt_pk_u8_f32 v123, v115, 3, v112
	v_cvt_pk_u8_f32 v104, v104, 3, v105
	v_cvt_pk_u8_f32 v105, v107, 3, v106
	v_cvt_pk_u8_f32 v106, v98, 3, v97
	v_cvt_pk_u8_f32 v107, v99, 3, v96
	v_cvt_pk_u8_f32 v88, v88, 3, v89
	v_cvt_pk_u8_f32 v89, v91, 3, v90
	v_cvt_pk_u8_f32 v90, v82, 3, v81
	v_cvt_pk_u8_f32 v91, v83, 3, v80
	v_cvt_pk_u8_f32 v72, v72, 3, v73
	v_cvt_pk_u8_f32 v73, v75, 3, v74
	v_cvt_pk_u8_f32 v74, v66, 3, v65
	v_cvt_pk_u8_f32 v75, v67, 3, v64
	v_cvt_pk_u8_f32 v58, v50, 3, v49
	v_addc_co_u32_e32 v49, vcc, 0, v173, vcc
	v_cvt_pk_u8_f32 v40, v40, 3, v41
	v_cvt_pk_u8_f32 v41, v43, 3, v42
	v_cvt_pk_u8_f32 v42, v34, 3, v33
	v_cvt_pk_u8_f32 v43, v35, 3, v32
	v_cvt_pk_u8_f32 v24, v24, 3, v25
	v_cvt_pk_u8_f32 v25, v27, 3, v26
	v_cvt_pk_u8_f32 v26, v18, 3, v17
	v_cvt_pk_u8_f32 v27, v19, 3, v16
	v_cvt_pk_u8_f32 v8, v8, 3, v9
	v_cvt_pk_u8_f32 v9, v11, 3, v10
	v_cvt_pk_u8_f32 v10, v2, 3, v1
	v_cvt_pk_u8_f32 v11, v3, 3, v0
	global_store_dwordx4 v[172:173], v[120:123], off sc1
	global_store_dwordx4 v[172:173], v[104:107], off offset:1024 sc1
	global_store_dwordx4 v[172:173], v[88:91], off offset:2048 sc1
	global_store_dwordx4 v[172:173], v[72:75], off offset:3072 sc1
	global_store_dwordx4 v[48:49], v[56:59], off sc1
	global_store_dwordx4 v[48:49], v[40:43], off offset:1024 sc1
	global_store_dwordx4 v[48:49], v[24:27], off offset:2048 sc1
	global_store_dwordx4 v[48:49], v[8:11], off offset:3072 sc1
